# layer 0: up-GEMM split (rounds 0-4 | 6th tile) with idle CUs running early ffnconv items; hand-written ffnconv for the rest
# speedup vs baseline: 1.0052x; 1.0052x over previous
.LU0_BB0_1163:
.LU0_BB0_1164:
	s_mov_b32 s30, s96
	s_waitcnt vmcnt(0)
	v_mov_b32_e32 v10, v154
	s_cmpk_gt_i32 s30, 0x4ff
	v_readfirstlane_b32 s5, v10
	s_cbranch_scc1 .LBB0_1094
	v_lshlrev_b32_e32 v1, 4, v10
	v_add_u32_e32 v2, 0x2000, v1
	v_ashrrev_i32_e32 v3, 31, v2
	v_lshrrev_b32_e32 v3, 22, v3
	v_add_u32_e32 v3, v2, v3
	v_ashrrev_i32_e32 v11, 10, v3
	v_mul_i32_i24_e32 v3, 0x400, v11
	v_sub_u32_e32 v2, v2, v3
	v_lshrrev_b32_e32 v3, 4, v2
	v_bitop3_b32 v2, v3, v2, 32 bitop3:0x6c
	v_ashrrev_i32_e32 v3, 31, v2
	v_lshrrev_b32_e32 v3, 26, v3
	v_add_u32_e32 v3, v2, v3
	v_lshlrev_b32_e32 v4, 3, v11
	v_ashrrev_i32_e32 v12, 6, v3
	v_and_b32_e32 v4, -16, v4
	v_add_u32_e32 v4, v12, v4
	v_and_b32_e32 v5, 3, v12
	s_mov_b32 s0, 0xfffe0
	v_lshrrev_b32_e32 v6, 2, v4
	v_lshlrev_b32_e32 v7, 1, v4
	v_and_b32_e32 v3, 0xc0, v3
	v_and_or_b32 v5, v4, s0, v5
	v_and_b32_e32 v6, 4, v6
	v_and_b32_e32 v7, 24, v7
	v_sub_u32_e32 v2, v2, v3
	v_mov_b32_e32 v3, 1
	v_or3_b32 v5, v5, v6, v7
	v_lshlrev_b32_e32 v6, 5, v11
	v_ashrrev_i16_sdwa v2, v3, sext(v2) dst_sel:DWORD dst_unused:UNUSED_PAD src0_sel:DWORD src1_sel:BYTE_0
	v_and_b32_e32 v6, 32, v6
	v_bfe_i32 v13, v2, 0, 16
	v_add_lshl_u32 v2, v6, v13, 1
	v_lshl_add_u32 v130, v5, 12, v2
	v_lshl_add_u32 v132, v4, 12, v2
	v_bfe_i32 v2, v10, 27, 1
	v_lshrrev_b32_e32 v2, 22, v2
	v_add_u32_e32 v2, v1, v2
	v_and_b32_e32 v2, 0xfffffc00, v2
	v_sub_u32_e32 v1, v1, v2
	v_lshrrev_b32_e32 v2, 4, v1
	v_bitop3_b32 v2, v2, v1, 32 bitop3:0x6c
	v_ashrrev_i32_e32 v1, 31, v1
	v_lshrrev_b32_e32 v1, 26, v1
	v_add_u32_e32 v1, v2, v1
	v_ashrrev_i32_e32 v14, 6, v1
	v_ashrrev_i32_e32 v1, 31, v10
	v_lshrrev_b32_e32 v1, 26, v1
	v_add_u32_e32 v1, v10, v1
	s_add_u32 s31, s90, 0x11918000
	v_ashrrev_i32_e32 v15, 6, v1
	s_addc_u32 s33, s91, 0
	v_lshlrev_b32_e32 v1, 3, v15
	s_add_u32 s34, s90, 0x8000000
	v_and_b32_e32 v1, -16, v1
	s_addc_u32 s35, s91, 0
	v_add_u32_e32 v1, v14, v1
	v_and_b32_e32 v4, 3, v14
	s_ashr_i32 s37, s30, 31
	v_and_or_b32 v4, v1, s0, v4
	s_lshr_b32 s0, s37, 29
	s_add_i32 s0, s30, s0
	s_ashr_i32 s6, s5, 6
	s_ashr_i32 s1, s0, 3
	s_and_b32 s0, s0, -8
	s_ashr_i32 s8, s5, 8
	s_lshl_b32 s36, s6, 10
	s_sub_i32 s0, s30, s0
	s_cmp_lt_i32 s0, 0
	s_movk_i32 s38, 0xb1
	s_cselect_b32 s2, s38, 0xb0
	s_mul_i32 s0, s2, s0
	s_add_i32 s0, s0, s1
	s_mul_hi_i32 s1, s0, 0x2e8ba2e9
	s_lshr_b32 s2, s1, 31
	s_ashr_i32 s1, s1, 6
	s_add_i32 s1, s1, s2
	s_lshl_b32 s2, s1, 3
	s_mulk_i32 s1, 0x160
	s_sub_i32 s0, s0, s1
	s_bfe_u32 s1, s0, 0x3001c
	s_add_i32 s1, s0, s1
	s_sext_i32_i16 s3, s1
	s_and_b32 s1, s1, 0xfff8
	s_sub_i32 s0, s0, s1
	s_sext_i32_i16 s0, s0
	s_add_i32 s18, s2, s0
	v_lshrrev_b32_e32 v5, 2, v1
	v_lshlrev_b32_e32 v6, 1, v1
	s_ashr_i32 s19, s18, 31
	v_and_b32_e32 v5, 4, v5
	v_and_b32_e32 v6, 24, v6
	s_lshr_b32 s4, s3, 3
	s_lshl_b64 s[0:1], s[18:19], 20
	v_or3_b32 v4, v4, v5, v6
	v_mul_i32_i24_e32 v6, 64, v14
	s_add_u32 s20, s31, s0
	v_sub_u32_e32 v2, v2, v6
	s_addc_u32 s21, s33, s1
	s_bfe_i64 s[0:1], s[4:5], 0x100000
	v_lshlrev_b32_e32 v5, 5, v15
	v_ashrrev_i16_sdwa v2, v3, sext(v2) dst_sel:DWORD dst_unused:UNUSED_PAD src0_sel:DWORD src1_sel:BYTE_0
	s_lshl_b64 s[0:1], s[0:1], 20
	v_and_b32_e32 v5, 32, v5
	v_bfe_i32 v16, v2, 0, 16
	s_add_u32 s24, s34, s0
	v_add_lshl_u32 v2, v5, v16, 1
	s_addc_u32 s25, s35, s1
	s_add_i32 s19, s36, 0
	v_lshl_add_u32 v134, v4, 12, v2
	s_add_i32 m0, s19, 0x10000
	v_lshl_add_u32 v136, v1, 12, v2
	global_load_lds_dwordx4 v134, s[24:25]
	s_add_i32 m0, s19, 0x12000
	s_add_u32 s0, s24, 0x80000
	global_load_lds_dwordx4 v130, s[24:25]
	s_addc_u32 s1, s25, 0
	s_add_i32 m0, s19, 0x14000
	s_add_i32 s39, s19, 0x2000
	global_load_lds_dwordx4 v134, s[0:1]
	s_add_i32 m0, s19, 0x16000
	v_mov_b32_e32 v135, 0
	global_load_lds_dwordx4 v130, s[0:1]
	s_mov_b32 m0, s19
	s_add_u32 s0, s20, 0x80000
	global_load_lds_dwordx4 v136, s[20:21]
	s_mov_b32 m0, s39
	s_addc_u32 s1, s21, 0
	s_add_i32 s40, s19, 0x4000
	global_load_lds_dwordx4 v132, s[20:21]
	s_mov_b32 m0, s40
	s_add_i32 s41, s19, 0x6000
	global_load_lds_dwordx4 v136, s[0:1]
	s_mov_b32 m0, s41
	v_mov_b32_e32 v131, v135
	global_load_lds_dwordx4 v132, s[0:1]
	v_mov_b32_e32 v137, v135
	v_mov_b32_e32 v133, v135
	s_cmp_eq_u32 s8, 1
	s_mov_b32 s22, 0
	v_lshl_add_u64 v[8:9], s[24:25], 0, v[134:135]
	v_lshl_add_u64 v[6:7], s[24:25], 0, v[130:131]
	v_lshl_add_u64 v[2:3], s[20:21], 0, v[136:137]
	s_cselect_b64 s[0:1], -1, 0
	s_cmp_lg_u32 s8, 1
	v_lshl_add_u64 v[4:5], s[20:21], 0, v[132:133]
	s_cbranch_scc1 .LU0_BB0_1167
	s_barrier
.LU0_BB0_1167:
	s_add_u32 s2, s90, 0x15918000
	s_addc_u32 s3, s91, 0
	s_lshl_b32 s6, s6, 5
	s_and_b32 s12, s6, 0x60
	s_mov_b64 s[6:7], 0x80
	s_add_i32 m0, s19, 0x18000
	v_lshl_add_u64 v[8:9], v[8:9], 0, s[6:7]
	s_lshl_b32 s9, s8, 13
	s_lshl_b32 s13, s12, 7
	s_waitcnt vmcnt(2)
	s_barrier
	global_load_lds_dwordx4 v[8:9], off
	v_lshl_add_u64 v[6:7], v[6:7], 0, s[6:7]
	s_add_i32 m0, s19, 0x1a000
	s_add_i32 s42, s19, 0x8000
	s_add_i32 s43, s19, 0xa000
	global_load_lds_dwordx4 v[6:7], off
	v_lshl_add_u64 v[2:3], v[2:3], 0, s[6:7]
	s_mov_b32 m0, s42
	s_add_u32 s10, s24, 0x80080
	global_load_lds_dwordx4 v[2:3], off
	v_lshl_add_u64 v[2:3], v[4:5], 0, s[6:7]
	s_mov_b32 m0, s43
	s_addc_u32 s11, s25, 0
	global_load_lds_dwordx4 v[2:3], off
	s_add_i32 m0, s19, 0x1c000
	v_lshl_add_u64 v[2:3], s[10:11], 0, v[134:135]
	global_load_lds_dwordx4 v[2:3], off
	v_lshl_add_u64 v[2:3], s[10:11], 0, v[130:131]
	s_add_i32 m0, s19, 0x1e000
	s_mov_b64 s[10:11], 0x80080
	global_load_lds_dwordx4 v[2:3], off
	v_lshrrev_b32_e32 v3, 1, v10
	v_and_b32_e32 v3, 24, v3
	v_and_b32_e32 v2, 15, v10
	v_lshlrev_b32_e32 v4, 1, v3
	v_lshl_or_b32 v1, s8, 6, v2
	v_lshl_or_b32 v2, v2, 6, v4
	v_lshlrev_b32_e32 v4, 2, v10
	v_and_b32_e32 v4, 32, v4
	v_bitop3_b32 v5, v2, s9, v4 bitop3:0xde
	v_bitop3_b32 v150, v2, s13, v4 bitop3:0xde
	v_lshlrev_b32_e32 v2, 15, v11
	v_and_b32_e32 v2, 0xffff0000, v2
	v_or_b32_e32 v151, s12, v3
	v_lshl_add_u32 v2, v12, 12, v2
	v_and_b32_e32 v3, 1, v11
	v_lshl_or_b32 v2, v3, 6, v2
	v_lshl_add_u32 v2, v13, 1, v2
	v_mov_b32_e32 v3, v135
	v_lshl_add_u64 v[138:139], v[2:3], 0, s[10:11]
	v_lshlrev_b32_e32 v2, 15, v15
	v_and_b32_e32 v2, 0xffff0000, v2
	v_lshl_add_u32 v2, v14, 12, v2
	v_and_b32_e32 v3, 1, v15
	s_waitcnt vmcnt(6)
	s_cmpk_lt_u32 s5, 0x100
	v_lshl_or_b32 v2, v3, 6, v2
	s_cselect_b64 s[8:9], -1, 0
	v_lshl_add_u32 v2, v16, 1, v2
	v_mov_b32_e32 v3, v135
	s_add_i32 s46, 0, 0x10000
	s_add_i32 s47, 0, 0x14000
	s_sext_i32_i16 s50, s4
	s_ashr_i32 s44, s94, 31
	s_mov_b32 s45, s94
	v_lshl_add_u64 v[140:141], v[2:3], 0, s[10:11]
	v_mov_b64_e32 v[142:143], 0x500
	v_mov_b64_e32 v[144:145], 0x4ff
	v_add_u32_e32 v152, s46, v150
	v_add_u32_e32 v153, s47, v150
	v_add_u32_e32 v155, 0, v5
	s_movk_i32 s48, 0x5800
	s_barrier
	s_branch .LU0_BB0_1170

.LU0_BB0_1179:
	s_waitcnt vmcnt(0)
	s_barrier
.LBB0_1094:
	s_cmp_gt_i32 s87, 8
	s_cbranch_scc1 .LBB0_1180
	s_load_dword s0, s[92:93], 0x104
	s_waitcnt lgkmcnt(0)
	s_cmp_lt_i32 s0, 9
	s_cbranch_scc1 .LBB0_1180
	s_cmp_eq_u32 s87, 8
	s_cbranch_scc1 .LBB0_1164
	s_cmp_lt_u32 s0, 23
	s_mov_b64 s[0:1], -1
	s_cbranch_scc0 .LBB0_1151
	s_getreg_b32 s2, hwreg(HW_REG_XCC_ID, 0, 4)
	s_waitcnt vmcnt(0)
	s_waitcnt vmcnt(0)
	s_barrier
	s_mov_b64 s[0:1], exec
	v_readlane_b32 s4, v232, 4
	v_readlane_b32 s5, v232, 5
	s_and_b64 s[4:5], s[0:1], s[4:5]
	s_mov_b64 exec, s[4:5]
	s_cbranch_execz .LBB0_1150
	s_add_i32 s3, 0, 0x20000
	v_mov_b32_e32 v1, s3
	s_waitcnt vmcnt(0) expcnt(0) lgkmcnt(0)
	ds_read_b32 v3, v1
	s_add_i32 s3, 0, 0x20004
	v_mov_b32_e32 v1, s3
	ds_read_b32 v1, v1
	s_and_b32 s33, s2, 15
	s_waitcnt lgkmcnt(1)
	v_cmp_ne_u32_e32 vcc, 0, v3
	s_cbranch_vccnz .LBB0_1114
	s_add_u32 s2, s90, 0x2c918200
	s_addc_u32 s3, s91, 0
	s_add_u32 s4, s90, 0x2c918400
	s_addc_u32 s5, s91, 0
	s_add_u32 s6, s90, 0x2c918500
	s_addc_u32 s7, s91, 0
	s_add_u32 s8, s90, 0x2c918600
	s_addc_u32 s9, s91, 0
	s_add_u32 s10, s90, 0x2c918700
	s_addc_u32 s11, s91, 0
	s_add_u32 s12, s90, 0x2c918800
	s_addc_u32 s13, s91, 0
	s_add_u32 s14, s90, 0x2c918900
	s_addc_u32 s15, s91, 0
	s_add_u32 s16, s90, 0x2c918a00
	s_addc_u32 s17, s91, 0
	s_add_u32 s18, s90, 0x2c918b00
	s_addc_u32 s19, s91, 0
	s_add_u32 s20, s90, 0x2c918c00
	s_addc_u32 s21, s91, 0
	s_add_u32 s22, s90, 0x2c918d00
	s_addc_u32 s23, s91, 0
	s_add_u32 s24, s90, 0x2c918e00
	s_addc_u32 s25, s91, 0
	s_add_u32 s26, s90, 0x2c918f00
	s_addc_u32 s27, s91, 0
	s_add_u32 s28, s90, 0x2c919000
	s_addc_u32 s29, s91, 0
	s_add_u32 s30, s90, 0x2c919100
	s_addc_u32 s31, s91, 0
	s_add_u32 s34, s90, 0x2c919200
	s_addc_u32 s35, s91, 0
	s_mul_i32 s44, s95, s97
	s_add_u32 s36, s90, 0x2c919300
	s_mul_i32 s44, s44, s94
	s_addc_u32 s37, s91, 0
	s_mov_b32 s45, 1
	v_mov_b32_e32 v17, 0
	s_branch .LBB0_1102

.LBB0_1163:
.LBB0_1164:
	s_add_u32 s30, s96, 0x500
	s_waitcnt vmcnt(0)
	v_mov_b32_e32 v10, v154
	s_cmpk_gt_i32 s30, 0x57f
	v_readfirstlane_b32 s5, v10
	s_cbranch_scc1 .Learly_p9
	v_lshlrev_b32_e32 v1, 4, v10
	v_add_u32_e32 v2, 0x2000, v1
	v_ashrrev_i32_e32 v3, 31, v2
	v_lshrrev_b32_e32 v3, 22, v3
	v_add_u32_e32 v3, v2, v3
	v_ashrrev_i32_e32 v11, 10, v3
	v_mul_i32_i24_e32 v3, 0x400, v11
	v_sub_u32_e32 v2, v2, v3
	v_lshrrev_b32_e32 v3, 4, v2
	v_bitop3_b32 v2, v3, v2, 32 bitop3:0x6c
	v_ashrrev_i32_e32 v3, 31, v2
	v_lshrrev_b32_e32 v3, 26, v3
	v_add_u32_e32 v3, v2, v3
	v_lshlrev_b32_e32 v4, 3, v11
	v_ashrrev_i32_e32 v12, 6, v3
	v_and_b32_e32 v4, -16, v4
	v_add_u32_e32 v4, v12, v4
	v_and_b32_e32 v5, 3, v12
	s_mov_b32 s0, 0xfffe0
	v_lshrrev_b32_e32 v6, 2, v4
	v_lshlrev_b32_e32 v7, 1, v4
	v_and_b32_e32 v3, 0xc0, v3
	v_and_or_b32 v5, v4, s0, v5
	v_and_b32_e32 v6, 4, v6
	v_and_b32_e32 v7, 24, v7
	v_sub_u32_e32 v2, v2, v3
	v_mov_b32_e32 v3, 1
	v_or3_b32 v5, v5, v6, v7
	v_lshlrev_b32_e32 v6, 5, v11
	v_ashrrev_i16_sdwa v2, v3, sext(v2) dst_sel:DWORD dst_unused:UNUSED_PAD src0_sel:DWORD src1_sel:BYTE_0
	v_and_b32_e32 v6, 32, v6
	v_bfe_i32 v13, v2, 0, 16
	v_add_lshl_u32 v2, v6, v13, 1
	v_lshl_add_u32 v130, v5, 12, v2
	v_lshl_add_u32 v132, v4, 12, v2
	v_bfe_i32 v2, v10, 27, 1
	v_lshrrev_b32_e32 v2, 22, v2
	v_add_u32_e32 v2, v1, v2
	v_and_b32_e32 v2, 0xfffffc00, v2
	v_sub_u32_e32 v1, v1, v2
	v_lshrrev_b32_e32 v2, 4, v1
	v_bitop3_b32 v2, v2, v1, 32 bitop3:0x6c
	v_ashrrev_i32_e32 v1, 31, v1
	v_lshrrev_b32_e32 v1, 26, v1
	v_add_u32_e32 v1, v2, v1
	v_ashrrev_i32_e32 v14, 6, v1
	v_ashrrev_i32_e32 v1, 31, v10
	v_lshrrev_b32_e32 v1, 26, v1
	v_add_u32_e32 v1, v10, v1
	s_add_u32 s31, s90, 0x11918000
	v_ashrrev_i32_e32 v15, 6, v1
	s_addc_u32 s33, s91, 0
	v_lshlrev_b32_e32 v1, 3, v15
	s_add_u32 s34, s90, 0x8000000
	v_and_b32_e32 v1, -16, v1
	s_addc_u32 s35, s91, 0
	v_add_u32_e32 v1, v14, v1
	v_and_b32_e32 v4, 3, v14
	s_ashr_i32 s37, s30, 31
	v_and_or_b32 v4, v1, s0, v4
	s_lshr_b32 s0, s37, 29
	s_add_i32 s0, s30, s0
	s_ashr_i32 s6, s5, 6
	s_ashr_i32 s1, s0, 3
	s_and_b32 s0, s0, -8
	s_ashr_i32 s8, s5, 8
	s_lshl_b32 s36, s6, 10
	s_sub_i32 s0, s30, s0
	s_cmp_lt_i32 s0, 0
	s_movk_i32 s38, 0xb1
	s_cselect_b32 s2, s38, 0xb0
	s_mul_i32 s0, s2, s0
	s_add_i32 s0, s0, s1
	s_mul_hi_i32 s1, s0, 0x2e8ba2e9
	s_lshr_b32 s2, s1, 31
	s_ashr_i32 s1, s1, 6
	s_add_i32 s1, s1, s2
	s_lshl_b32 s2, s1, 3
	s_mulk_i32 s1, 0x160
	s_sub_i32 s0, s0, s1
	s_bfe_u32 s1, s0, 0x3001c
	s_add_i32 s1, s0, s1
	s_sext_i32_i16 s3, s1
	s_and_b32 s1, s1, 0xfff8
	s_sub_i32 s0, s0, s1
	s_sext_i32_i16 s0, s0
	s_add_i32 s18, s2, s0
	v_lshrrev_b32_e32 v5, 2, v1
	v_lshlrev_b32_e32 v6, 1, v1
	s_ashr_i32 s19, s18, 31
	v_and_b32_e32 v5, 4, v5
	v_and_b32_e32 v6, 24, v6
	s_lshr_b32 s4, s3, 3
	s_lshl_b64 s[0:1], s[18:19], 20
	v_or3_b32 v4, v4, v5, v6
	v_mul_i32_i24_e32 v6, 64, v14
	s_add_u32 s20, s31, s0
	v_sub_u32_e32 v2, v2, v6
	s_addc_u32 s21, s33, s1
	s_bfe_i64 s[0:1], s[4:5], 0x100000
	v_lshlrev_b32_e32 v5, 5, v15
	v_ashrrev_i16_sdwa v2, v3, sext(v2) dst_sel:DWORD dst_unused:UNUSED_PAD src0_sel:DWORD src1_sel:BYTE_0
	s_lshl_b64 s[0:1], s[0:1], 20
	v_and_b32_e32 v5, 32, v5
	v_bfe_i32 v16, v2, 0, 16
	s_add_u32 s24, s34, s0
	v_add_lshl_u32 v2, v5, v16, 1
	s_addc_u32 s25, s35, s1
	s_add_i32 s19, s36, 0
	v_lshl_add_u32 v134, v4, 12, v2
	s_add_i32 m0, s19, 0x10000
	v_lshl_add_u32 v136, v1, 12, v2
	global_load_lds_dwordx4 v134, s[24:25]
	s_add_i32 m0, s19, 0x12000
	s_add_u32 s0, s24, 0x80000
	global_load_lds_dwordx4 v130, s[24:25]
	s_addc_u32 s1, s25, 0
	s_add_i32 m0, s19, 0x14000
	s_add_i32 s39, s19, 0x2000
	global_load_lds_dwordx4 v134, s[0:1]
	s_add_i32 m0, s19, 0x16000
	v_mov_b32_e32 v135, 0
	global_load_lds_dwordx4 v130, s[0:1]
	s_mov_b32 m0, s19
	s_add_u32 s0, s20, 0x80000
	global_load_lds_dwordx4 v136, s[20:21]
	s_mov_b32 m0, s39
	s_addc_u32 s1, s21, 0
	s_add_i32 s40, s19, 0x4000
	global_load_lds_dwordx4 v132, s[20:21]
	s_mov_b32 m0, s40
	s_add_i32 s41, s19, 0x6000
	global_load_lds_dwordx4 v136, s[0:1]
	s_mov_b32 m0, s41
	v_mov_b32_e32 v131, v135
	global_load_lds_dwordx4 v132, s[0:1]
	v_mov_b32_e32 v137, v135
	v_mov_b32_e32 v133, v135
	s_cmp_eq_u32 s8, 1
	s_mov_b32 s22, 0
	v_lshl_add_u64 v[8:9], s[24:25], 0, v[134:135]
	v_lshl_add_u64 v[6:7], s[24:25], 0, v[130:131]
	v_lshl_add_u64 v[2:3], s[20:21], 0, v[136:137]
	s_cselect_b64 s[0:1], -1, 0
	s_cmp_lg_u32 s8, 1
	v_lshl_add_u64 v[4:5], s[20:21], 0, v[132:133]
	s_cbranch_scc1 .LBB0_1167
	s_barrier

.LBB0_1179:
	s_waitcnt vmcnt(0)
	s_barrier
	s_branch .LBB0_1180
.Learly_p9:
	s_load_dwordx4 s[0:3], s[92:93], 0xd8
	s_add_u32 s38, s90, 0x15918000
	s_addc_u32 s39, s91, 0
	s_add_u32 s40, s90, 0x21918000
	s_addc_u32 s41, s91, 0
	s_add_u32 s4, s90, 0x2c918080
	s_addc_u32 s5, s91, 0
	v_mov_b32_e32 v4, 0xbfb8aa3b
	v_mov_b32_e32 v5, 0xbfb8aa3b
	v_mov_b32_e32 v6, 1.0
	v_mov_b32_e32 v7, 1.0
	v_mov_b32_e32 v9, 0
	v_mov_b32_e32 v208, 1
	s_waitcnt lgkmcnt(0)
	v_readfirstlane_b32 s6, v154
	s_lshr_b32 s6, s6, 6
	s_sub_u32 s35, s96, 128
	s_lshl_b32 s35, s35, 3
	s_add_u32 s6, s6, s35
	s_mul_i32 s33, s6, 52429
	s_lshr_b32 s33, s33, 21
	s_mul_i32 s34, s33, 40
	s_sub_u32 s43, s6, s34
	s_and_b32 s34, s33, 1
	s_bfe_u32 s35, s33, 0x20001
	s_lshr_b32 s36, s33, 3
	s_cmp_lg_u32 s35, 0
	s_cselect_b32 s28, -1, 0
	s_cmp_lg_u32 s35, 3
	s_cselect_b32 s29, -1, 0
	s_cmp_lg_u32 s34, 0
	s_cselect_b32 s30, -1, 0
	s_cselect_b32 s31, 0, -1
	s_lshl_b32 s36, s36, 10
	s_lshl_b32 s35, s35, 8
	s_lshl_b32 s34, s34, 5
	s_add_u32 s36, s36, s35
	s_add_u32 s36, s36, s34
	s_add_u32 s36, s36, 4096
	v_and_b32_e32 v1, 63, v154
	v_lshlrev_b32_e32 v1, 2, v1
	s_lshl_b32 s33, s43, 8
	v_add_u32_e32 v1, s33, v1
	v_add_u32_e32 v2, 0x2c00, v1
	v_lshlrev_b32_e32 v3, 1, v1
	s_add_i32 s33, s36, 0
	s_mul_i32 s33, s33, 0x2c00
	s_add_u32 s20, s40, s33
	s_addc_u32 s21, s41, 0
	s_add_i32 s33, s36, 64
	s_mul_i32 s33, s33, 0x2c00
	s_add_u32 s22, s40, s33
	s_addc_u32 s23, s41, 0
	s_add_i32 s33, s36, 128
	s_mul_i32 s33, s33, 0x2c00
	s_add_u32 s24, s40, s33
	s_addc_u32 s25, s41, 0
	s_add_i32 s33, s36, 192
	s_mul_i32 s33, s33, 0x2c00
	s_add_u32 s26, s40, s33
	s_addc_u32 s27, s41, 0
	s_add_i32 s33, s36, -65
	s_mul_i32 s33, s33, 0x5800
	s_ashr_i32 s34, s33, 31
	s_add_u32 s8, s38, s33
	s_addc_u32 s9, s39, s34
	s_add_i32 s33, s36, -1
	s_mul_i32 s33, s33, 0x5800
	s_ashr_i32 s34, s33, 31
	s_add_u32 s10, s38, s33
	s_addc_u32 s11, s39, s34
	s_add_i32 s33, s36, 63
	s_mul_i32 s33, s33, 0x5800
	s_ashr_i32 s34, s33, 31
	s_add_u32 s12, s38, s33
	s_addc_u32 s13, s39, s34
	s_add_i32 s33, s36, 127
	s_mul_i32 s33, s33, 0x5800
	s_ashr_i32 s34, s33, 31
	s_add_u32 s14, s38, s33
	s_addc_u32 s15, s39, s34
	s_add_i32 s33, s36, 191
	s_mul_i32 s33, s33, 0x5800
	s_ashr_i32 s34, s33, 31
	s_add_u32 s16, s38, s33
	s_addc_u32 s17, s39, s34
	s_add_i32 s33, s36, 255
	s_mul_i32 s33, s33, 0x5800
	s_ashr_i32 s34, s33, 31
	s_add_u32 s18, s38, s33
	s_addc_u32 s19, s39, s34
	s_add_u32 s33, s0, 0x0
	s_addc_u32 s34, s1, 0
	s_mov_b32 s36, s33
	s_mov_b32 s37, s34
	global_load_dwordx2 v[10:11], v3, s[36:37]
	s_add_u32 s36, s36, 0x5800
	s_addc_u32 s37, s37, 0
	global_load_dwordx2 v[28:29], v3, s[36:37]
	s_add_u32 s33, s0, 0xb000
	s_addc_u32 s34, s1, 0
	s_mov_b32 s36, s33
	s_mov_b32 s37, s34
	global_load_dwordx2 v[12:13], v3, s[36:37]
	s_add_u32 s36, s36, 0x5800
	s_addc_u32 s37, s37, 0
	global_load_dwordx2 v[30:31], v3, s[36:37]
	s_add_u32 s33, s0, 0x16000
	s_addc_u32 s34, s1, 0
	s_mov_b32 s36, s33
	s_mov_b32 s37, s34
	global_load_dwordx2 v[14:15], v3, s[36:37]
	s_add_u32 s36, s36, 0x5800
	s_addc_u32 s37, s37, 0
	global_load_dwordx2 v[32:33], v3, s[36:37]
	s_add_u32 s33, s0, 0x21000
	s_addc_u32 s34, s1, 0
	s_mov_b32 s36, s33
	s_mov_b32 s37, s34
	global_load_dwordx2 v[16:17], v3, s[36:37]
	s_add_u32 s36, s36, 0x5800
	s_addc_u32 s37, s37, 0
	global_load_dwordx2 v[34:35], v3, s[36:37]
	s_add_u32 s33, s0, 0x2c000
	s_addc_u32 s34, s1, 0
	s_mov_b32 s36, s33
	s_mov_b32 s37, s34
	global_load_dwordx2 v[18:19], v3, s[36:37]
	s_add_u32 s36, s36, 0x5800
	s_addc_u32 s37, s37, 0
	global_load_dwordx2 v[36:37], v3, s[36:37]
	s_add_u32 s33, s0, 0x37000
	s_addc_u32 s34, s1, 0
	s_mov_b32 s36, s33
	s_mov_b32 s37, s34
	global_load_dwordx2 v[20:21], v3, s[36:37]
	s_add_u32 s36, s36, 0x5800
	s_addc_u32 s37, s37, 0
	global_load_dwordx2 v[38:39], v3, s[36:37]
	s_add_u32 s33, s0, 0x42000
	s_addc_u32 s34, s1, 0
	s_mov_b32 s36, s33
	s_mov_b32 s37, s34
	global_load_dwordx2 v[22:23], v3, s[36:37]
	s_add_u32 s36, s36, 0x5800
	s_addc_u32 s37, s37, 0
	global_load_dwordx2 v[40:41], v3, s[36:37]
	s_add_u32 s33, s0, 0x4d000
	s_addc_u32 s34, s1, 0
	s_mov_b32 s36, s33
	s_mov_b32 s37, s34
	global_load_dwordx2 v[24:25], v3, s[36:37]
	s_add_u32 s36, s36, 0x5800
	s_addc_u32 s37, s37, 0
	global_load_dwordx2 v[42:43], v3, s[36:37]
	s_add_u32 s33, s0, 0x58000
	s_addc_u32 s34, s1, 0
	s_mov_b32 s36, s33
	s_mov_b32 s37, s34
	global_load_dwordx2 v[26:27], v3, s[36:37]
	s_add_u32 s36, s36, 0x5800
	s_addc_u32 s37, s37, 0
	global_load_dwordx2 v[44:45], v3, s[36:37]
	global_load_dwordx2 v[46:47], v3, s[2:3]
	s_add_u32 s36, s2, 0x5800
	s_addc_u32 s37, s3, 0
	global_load_dwordx2 v[48:49], v3, s[36:37]
	global_load_dword v180, v1, s[8:9]
	global_load_dword v181, v2, s[8:9]
	global_load_dword v182, v1, s[10:11]
	global_load_dword v183, v2, s[10:11]
	global_load_dword v184, v1, s[12:13]
	global_load_dword v185, v2, s[12:13]
	global_load_dword v186, v1, s[14:15]
	global_load_dword v187, v2, s[14:15]
	global_load_dword v188, v1, s[16:17]
	global_load_dword v189, v2, s[16:17]
	global_load_dword v190, v1, s[18:19]
	global_load_dword v191, v2, s[18:19]
	s_add_u32 s8, s8, 0x5800
	s_addc_u32 s9, s9, 0
	s_add_u32 s10, s10, 0x5800
	s_addc_u32 s11, s11, 0
	s_add_u32 s12, s12, 0x5800
	s_addc_u32 s13, s13, 0
	s_add_u32 s14, s14, 0x5800
	s_addc_u32 s15, s15, 0
	s_add_u32 s16, s16, 0x5800
	s_addc_u32 s17, s17, 0
	s_add_u32 s18, s18, 0x5800
	s_addc_u32 s19, s19, 0
	global_load_dword v192, v1, s[8:9]
	global_load_dword v193, v2, s[8:9]
	global_load_dword v194, v1, s[10:11]
	global_load_dword v195, v2, s[10:11]
	global_load_dword v196, v1, s[12:13]
	global_load_dword v197, v2, s[12:13]
	global_load_dword v198, v1, s[14:15]
	global_load_dword v199, v2, s[14:15]
	global_load_dword v200, v1, s[16:17]
	global_load_dword v201, v2, s[16:17]
	global_load_dword v202, v1, s[18:19]
	global_load_dword v203, v2, s[18:19]
	s_add_u32 s8, s8, 0x5800
	s_addc_u32 s9, s9, 0
	s_add_u32 s10, s10, 0x5800
	s_addc_u32 s11, s11, 0
	s_add_u32 s12, s12, 0x5800
	s_addc_u32 s13, s13, 0
	s_add_u32 s14, s14, 0x5800
	s_addc_u32 s15, s15, 0
	s_add_u32 s16, s16, 0x5800
	s_addc_u32 s17, s17, 0
	s_add_u32 s18, s18, 0x5800
	s_addc_u32 s19, s19, 0
	global_load_dword v156, v1, s[8:9]
	global_load_dword v157, v2, s[8:9]
	global_load_dword v158, v1, s[10:11]
	global_load_dword v159, v2, s[10:11]
	global_load_dword v160, v1, s[12:13]
	global_load_dword v161, v2, s[12:13]
	global_load_dword v162, v1, s[14:15]
	global_load_dword v163, v2, s[14:15]
	global_load_dword v164, v1, s[16:17]
	global_load_dword v165, v2, s[16:17]
	global_load_dword v166, v1, s[18:19]
	global_load_dword v167, v2, s[18:19]
	s_add_u32 s8, s8, 0x5800
	s_addc_u32 s9, s9, 0
	s_add_u32 s10, s10, 0x5800
	s_addc_u32 s11, s11, 0
	s_add_u32 s12, s12, 0x5800
	s_addc_u32 s13, s13, 0
	s_add_u32 s14, s14, 0x5800
	s_addc_u32 s15, s15, 0
	s_add_u32 s16, s16, 0x5800
	s_addc_u32 s17, s17, 0
	s_add_u32 s18, s18, 0x5800
	s_addc_u32 s19, s19, 0
	global_load_dword v168, v1, s[8:9]
	global_load_dword v169, v2, s[8:9]
	global_load_dword v170, v1, s[10:11]
	global_load_dword v171, v2, s[10:11]
	global_load_dword v172, v1, s[12:13]
	global_load_dword v173, v2, s[12:13]
	global_load_dword v174, v1, s[14:15]
	global_load_dword v175, v2, s[14:15]
	global_load_dword v176, v1, s[16:17]
	global_load_dword v177, v2, s[16:17]
	global_load_dword v178, v1, s[18:19]
	global_load_dword v179, v2, s[18:19]
	s_add_u32 s8, s8, 0x5800
	s_addc_u32 s9, s9, 0
	s_add_u32 s10, s10, 0x5800
	s_addc_u32 s11, s11, 0
	s_add_u32 s12, s12, 0x5800
	s_addc_u32 s13, s13, 0
	s_add_u32 s14, s14, 0x5800
	s_addc_u32 s15, s15, 0
	s_add_u32 s16, s16, 0x5800
	s_addc_u32 s17, s17, 0
	s_add_u32 s18, s18, 0x5800
	s_addc_u32 s19, s19, 0
	s_waitcnt vmcnt(24)
	v_and_b32_e32 v180, s30, v180
	v_and_b32_e32 v181, s30, v181
	v_and_b32_e32 v180, s28, v180
	v_and_b32_e32 v181, s28, v181
	v_lshlrev_b32_e32 v50, 16, v180
	v_and_b32_e32 v51, 0xffff0000, v180
	v_lshlrev_b32_e32 v52, 16, v181
	v_and_b32_e32 v53, 0xffff0000, v181
	v_and_b32_e32 v182, s30, v182
	v_and_b32_e32 v183, s30, v183
	v_lshlrev_b32_e32 v54, 16, v182
	v_and_b32_e32 v55, 0xffff0000, v182
	v_lshlrev_b32_e32 v56, 16, v183
	v_and_b32_e32 v57, 0xffff0000, v183
	v_and_b32_e32 v184, s30, v184
	v_and_b32_e32 v185, s30, v185
	v_lshlrev_b32_e32 v58, 16, v184
	v_and_b32_e32 v59, 0xffff0000, v184
	v_lshlrev_b32_e32 v60, 16, v185
	v_and_b32_e32 v61, 0xffff0000, v185
	v_and_b32_e32 v186, s30, v186
	v_and_b32_e32 v187, s30, v187
	v_lshlrev_b32_e32 v62, 16, v186
	v_and_b32_e32 v63, 0xffff0000, v186
	v_lshlrev_b32_e32 v64, 16, v187
	v_and_b32_e32 v65, 0xffff0000, v187
	v_and_b32_e32 v188, s30, v188
	v_and_b32_e32 v189, s30, v189
	v_lshlrev_b32_e32 v66, 16, v188
	v_and_b32_e32 v67, 0xffff0000, v188
	v_lshlrev_b32_e32 v68, 16, v189
	v_and_b32_e32 v69, 0xffff0000, v189
	v_and_b32_e32 v190, s30, v190
	v_and_b32_e32 v191, s30, v191
	v_and_b32_e32 v190, s29, v190
	v_and_b32_e32 v191, s29, v191
	v_lshlrev_b32_e32 v70, 16, v190
	v_and_b32_e32 v71, 0xffff0000, v190
	v_lshlrev_b32_e32 v72, 16, v191
	v_and_b32_e32 v73, 0xffff0000, v191
	v_and_b32_e32 v192, s28, v192
	v_and_b32_e32 v193, s28, v193
	v_lshlrev_b32_e32 v74, 16, v192
	v_and_b32_e32 v75, 0xffff0000, v192
	v_lshlrev_b32_e32 v76, 16, v193
	v_and_b32_e32 v77, 0xffff0000, v193
	v_lshlrev_b32_e32 v78, 16, v194
	v_and_b32_e32 v79, 0xffff0000, v194
	v_lshlrev_b32_e32 v80, 16, v195
	v_and_b32_e32 v81, 0xffff0000, v195
	v_lshlrev_b32_e32 v82, 16, v196
	v_and_b32_e32 v83, 0xffff0000, v196
	v_lshlrev_b32_e32 v84, 16, v197
	v_and_b32_e32 v85, 0xffff0000, v197
	v_lshlrev_b32_e32 v86, 16, v198
	v_and_b32_e32 v87, 0xffff0000, v198
	v_lshlrev_b32_e32 v88, 16, v199
	v_and_b32_e32 v89, 0xffff0000, v199
	v_lshlrev_b32_e32 v90, 16, v200
	v_and_b32_e32 v91, 0xffff0000, v200
	v_lshlrev_b32_e32 v92, 16, v201
	v_and_b32_e32 v93, 0xffff0000, v201
	v_and_b32_e32 v202, s29, v202
	v_and_b32_e32 v203, s29, v203
	v_lshlrev_b32_e32 v94, 16, v202
	v_and_b32_e32 v95, 0xffff0000, v202
	v_lshlrev_b32_e32 v96, 16, v203
	v_and_b32_e32 v97, 0xffff0000, v203
	global_load_dword v180, v1, s[8:9]
	global_load_dword v181, v2, s[8:9]
	global_load_dword v182, v1, s[10:11]
	global_load_dword v183, v2, s[10:11]
	global_load_dword v184, v1, s[12:13]
	global_load_dword v185, v2, s[12:13]
	global_load_dword v186, v1, s[14:15]
	global_load_dword v187, v2, s[14:15]
	global_load_dword v188, v1, s[16:17]
	global_load_dword v189, v2, s[16:17]
	global_load_dword v190, v1, s[18:19]
	global_load_dword v191, v2, s[18:19]
	s_add_u32 s8, s8, 0x5800
	s_addc_u32 s9, s9, 0
	s_add_u32 s10, s10, 0x5800
	s_addc_u32 s11, s11, 0
	s_add_u32 s12, s12, 0x5800
	s_addc_u32 s13, s13, 0
	s_add_u32 s14, s14, 0x5800
	s_addc_u32 s15, s15, 0
	s_add_u32 s16, s16, 0x5800
	s_addc_u32 s17, s17, 0
	s_add_u32 s18, s18, 0x5800
	s_addc_u32 s19, s19, 0
	global_load_dword v192, v1, s[8:9]
	global_load_dword v193, v2, s[8:9]
	global_load_dword v194, v1, s[10:11]
	global_load_dword v195, v2, s[10:11]
	global_load_dword v196, v1, s[12:13]
	global_load_dword v197, v2, s[12:13]
	global_load_dword v198, v1, s[14:15]
	global_load_dword v199, v2, s[14:15]
	global_load_dword v200, v1, s[16:17]
	global_load_dword v201, v2, s[16:17]
	global_load_dword v202, v1, s[18:19]
	global_load_dword v203, v2, s[18:19]
	s_add_u32 s8, s8, 0x5800
	s_addc_u32 s9, s9, 0
	s_add_u32 s10, s10, 0x5800
	s_addc_u32 s11, s11, 0
	s_add_u32 s12, s12, 0x5800
	s_addc_u32 s13, s13, 0
	s_add_u32 s14, s14, 0x5800
	s_addc_u32 s15, s15, 0
	s_add_u32 s16, s16, 0x5800
	s_addc_u32 s17, s17, 0
	s_add_u32 s18, s18, 0x5800
	s_addc_u32 s19, s19, 0
	s_mov_b32 s32, 0

.Lffn_p9e_skipld8:
	v_pk_fma_f32 v[146:147], v[10:11], v[98:99], v[46:47]
	v_pk_fma_f32 v[148:149], v[28:29], v[100:101], v[48:49]
	v_pk_fma_f32 v[146:147], v[12:13], v[122:123], v[146:147]
	v_pk_fma_f32 v[148:149], v[30:31], v[124:125], v[148:149]
	v_pk_fma_f32 v[146:147], v[14:15], v[50:51], v[146:147]
	v_pk_fma_f32 v[148:149], v[32:33], v[52:53], v[148:149]
	v_pk_fma_f32 v[146:147], v[16:17], v[102:103], v[146:147]
	v_pk_fma_f32 v[148:149], v[34:35], v[104:105], v[148:149]
	v_pk_fma_f32 v[146:147], v[18:19], v[126:127], v[146:147]
	v_pk_fma_f32 v[148:149], v[36:37], v[128:129], v[148:149]
	v_pk_fma_f32 v[146:147], v[20:21], v[54:55], v[146:147]
	v_pk_fma_f32 v[148:149], v[38:39], v[56:57], v[148:149]
	v_pk_fma_f32 v[146:147], v[22:23], v[106:107], v[146:147]
	v_pk_fma_f32 v[148:149], v[40:41], v[108:109], v[148:149]
	v_pk_fma_f32 v[146:147], v[24:25], v[130:131], v[146:147]
	v_pk_fma_f32 v[148:149], v[42:43], v[132:133], v[148:149]
	v_pk_fma_f32 v[146:147], v[26:27], v[58:59], v[146:147]
	v_pk_fma_f32 v[148:149], v[44:45], v[60:61], v[148:149]
	v_pk_mul_f32 v[150:151], v[146:147], v[4:5]
	v_exp_f32_e32 v150, v150
	v_exp_f32_e32 v151, v151
	s_nop 0
	v_pk_add_f32 v[150:151], v[150:151], v[6:7]
	v_rcp_f32_e32 v150, v150
	v_rcp_f32_e32 v151, v151
	s_nop 0
	v_pk_mul_f32 v[150:151], v[150:151], v[146:147]
	v_pk_mul_f32 v[150:151], v[150:151], v[148:149]
	v_cvt_pk_bf16_f32 v204, v150, v151
	global_store_dword v1, v204, s[20:21]
	v_pk_fma_f32 v[146:147], v[10:11], v[102:103], v[46:47]
	v_pk_fma_f32 v[148:149], v[28:29], v[104:105], v[48:49]
	v_pk_fma_f32 v[146:147], v[12:13], v[126:127], v[146:147]
	v_pk_fma_f32 v[148:149], v[30:31], v[128:129], v[148:149]
	v_pk_fma_f32 v[146:147], v[14:15], v[54:55], v[146:147]
	v_pk_fma_f32 v[148:149], v[32:33], v[56:57], v[148:149]
	v_pk_fma_f32 v[146:147], v[16:17], v[106:107], v[146:147]
	v_pk_fma_f32 v[148:149], v[34:35], v[108:109], v[148:149]
	v_pk_fma_f32 v[146:147], v[18:19], v[130:131], v[146:147]
	v_pk_fma_f32 v[148:149], v[36:37], v[132:133], v[148:149]
	v_pk_fma_f32 v[146:147], v[20:21], v[58:59], v[146:147]
	v_pk_fma_f32 v[148:149], v[38:39], v[60:61], v[148:149]
	v_pk_fma_f32 v[146:147], v[22:23], v[110:111], v[146:147]
	v_pk_fma_f32 v[148:149], v[40:41], v[112:113], v[148:149]
	v_pk_fma_f32 v[146:147], v[24:25], v[134:135], v[146:147]
	v_pk_fma_f32 v[148:149], v[42:43], v[136:137], v[148:149]
	v_pk_fma_f32 v[146:147], v[26:27], v[62:63], v[146:147]
	v_pk_fma_f32 v[148:149], v[44:45], v[64:65], v[148:149]
	v_pk_mul_f32 v[150:151], v[146:147], v[4:5]
	v_exp_f32_e32 v150, v150
	v_exp_f32_e32 v151, v151
	s_nop 0
	v_pk_add_f32 v[150:151], v[150:151], v[6:7]
	v_rcp_f32_e32 v150, v150
	v_rcp_f32_e32 v151, v151
	s_nop 0
	v_pk_mul_f32 v[150:151], v[150:151], v[146:147]
	v_pk_mul_f32 v[150:151], v[150:151], v[148:149]
	v_cvt_pk_bf16_f32 v205, v150, v151
	global_store_dword v1, v205, s[22:23]
	v_pk_fma_f32 v[146:147], v[10:11], v[106:107], v[46:47]
	v_pk_fma_f32 v[148:149], v[28:29], v[108:109], v[48:49]
	v_pk_fma_f32 v[146:147], v[12:13], v[130:131], v[146:147]
	v_pk_fma_f32 v[148:149], v[30:31], v[132:133], v[148:149]
	v_pk_fma_f32 v[146:147], v[14:15], v[58:59], v[146:147]
	v_pk_fma_f32 v[148:149], v[32:33], v[60:61], v[148:149]
	v_pk_fma_f32 v[146:147], v[16:17], v[110:111], v[146:147]
	v_pk_fma_f32 v[148:149], v[34:35], v[112:113], v[148:149]
	v_pk_fma_f32 v[146:147], v[18:19], v[134:135], v[146:147]
	v_pk_fma_f32 v[148:149], v[36:37], v[136:137], v[148:149]
	v_pk_fma_f32 v[146:147], v[20:21], v[62:63], v[146:147]
	v_pk_fma_f32 v[148:149], v[38:39], v[64:65], v[148:149]
	v_pk_fma_f32 v[146:147], v[22:23], v[114:115], v[146:147]
	v_pk_fma_f32 v[148:149], v[40:41], v[116:117], v[148:149]
	v_pk_fma_f32 v[146:147], v[24:25], v[138:139], v[146:147]
	v_pk_fma_f32 v[148:149], v[42:43], v[140:141], v[148:149]
	v_pk_fma_f32 v[146:147], v[26:27], v[66:67], v[146:147]
	v_pk_fma_f32 v[148:149], v[44:45], v[68:69], v[148:149]
	v_pk_mul_f32 v[150:151], v[146:147], v[4:5]
	v_exp_f32_e32 v150, v150
	v_exp_f32_e32 v151, v151
	s_nop 0
	v_pk_add_f32 v[150:151], v[150:151], v[6:7]
	v_rcp_f32_e32 v150, v150
	v_rcp_f32_e32 v151, v151
	s_nop 0
	v_pk_mul_f32 v[150:151], v[150:151], v[146:147]
	v_pk_mul_f32 v[150:151], v[150:151], v[148:149]
	v_cvt_pk_bf16_f32 v206, v150, v151
	global_store_dword v1, v206, s[24:25]
	v_pk_fma_f32 v[146:147], v[10:11], v[110:111], v[46:47]
	v_pk_fma_f32 v[148:149], v[28:29], v[112:113], v[48:49]
	v_pk_fma_f32 v[146:147], v[12:13], v[134:135], v[146:147]
	v_pk_fma_f32 v[148:149], v[30:31], v[136:137], v[148:149]
	v_pk_fma_f32 v[146:147], v[14:15], v[62:63], v[146:147]
	v_pk_fma_f32 v[148:149], v[32:33], v[64:65], v[148:149]
	v_pk_fma_f32 v[146:147], v[16:17], v[114:115], v[146:147]
	v_pk_fma_f32 v[148:149], v[34:35], v[116:117], v[148:149]
	v_pk_fma_f32 v[146:147], v[18:19], v[138:139], v[146:147]
	v_pk_fma_f32 v[148:149], v[36:37], v[140:141], v[148:149]
	v_pk_fma_f32 v[146:147], v[20:21], v[66:67], v[146:147]
	v_pk_fma_f32 v[148:149], v[38:39], v[68:69], v[148:149]
	v_pk_fma_f32 v[146:147], v[22:23], v[118:119], v[146:147]
	v_pk_fma_f32 v[148:149], v[40:41], v[120:121], v[148:149]
	v_pk_fma_f32 v[146:147], v[24:25], v[142:143], v[146:147]
	v_pk_fma_f32 v[148:149], v[42:43], v[144:145], v[148:149]
	v_pk_fma_f32 v[146:147], v[26:27], v[70:71], v[146:147]
	v_pk_fma_f32 v[148:149], v[44:45], v[72:73], v[148:149]
	v_pk_mul_f32 v[150:151], v[146:147], v[4:5]
	v_exp_f32_e32 v150, v150
	v_exp_f32_e32 v151, v151
	s_nop 0
	v_pk_add_f32 v[150:151], v[150:151], v[6:7]
	v_rcp_f32_e32 v150, v150
	v_rcp_f32_e32 v151, v151
	s_nop 0
	v_pk_mul_f32 v[150:151], v[150:151], v[146:147]
	v_pk_mul_f32 v[150:151], v[150:151], v[148:149]
	v_cvt_pk_bf16_f32 v207, v150, v151
	global_store_dword v1, v207, s[26:27]
	s_add_u32 s20, s20, 0x2c00
	s_addc_u32 s21, s21, 0
	s_add_u32 s22, s22, 0x2c00
	s_addc_u32 s23, s23, 0
	s_add_u32 s24, s24, 0x2c00
	s_addc_u32 s25, s25, 0
	s_add_u32 s26, s26, 0x2c00
	s_addc_u32 s27, s27, 0
	v_pk_fma_f32 v[146:147], v[10:11], v[122:123], v[46:47]
	v_pk_fma_f32 v[148:149], v[28:29], v[124:125], v[48:49]
	v_pk_fma_f32 v[146:147], v[12:13], v[50:51], v[146:147]
	v_pk_fma_f32 v[148:149], v[30:31], v[52:53], v[148:149]
	v_pk_fma_f32 v[146:147], v[14:15], v[74:75], v[146:147]
	v_pk_fma_f32 v[148:149], v[32:33], v[76:77], v[148:149]
	v_pk_fma_f32 v[146:147], v[16:17], v[126:127], v[146:147]
	v_pk_fma_f32 v[148:149], v[34:35], v[128:129], v[148:149]
	v_pk_fma_f32 v[146:147], v[18:19], v[54:55], v[146:147]
	v_pk_fma_f32 v[148:149], v[36:37], v[56:57], v[148:149]
	v_pk_fma_f32 v[146:147], v[20:21], v[78:79], v[146:147]
	v_pk_fma_f32 v[148:149], v[38:39], v[80:81], v[148:149]
	v_pk_fma_f32 v[146:147], v[22:23], v[130:131], v[146:147]
	v_pk_fma_f32 v[148:149], v[40:41], v[132:133], v[148:149]
	v_pk_fma_f32 v[146:147], v[24:25], v[58:59], v[146:147]
	v_pk_fma_f32 v[148:149], v[42:43], v[60:61], v[148:149]
	v_pk_fma_f32 v[146:147], v[26:27], v[82:83], v[146:147]
	v_pk_fma_f32 v[148:149], v[44:45], v[84:85], v[148:149]
	v_pk_mul_f32 v[150:151], v[146:147], v[4:5]
	v_exp_f32_e32 v150, v150
	v_exp_f32_e32 v151, v151
	s_nop 0
	v_pk_add_f32 v[150:151], v[150:151], v[6:7]
	v_rcp_f32_e32 v150, v150
	v_rcp_f32_e32 v151, v151
	s_nop 0
	v_pk_mul_f32 v[150:151], v[150:151], v[146:147]
	v_pk_mul_f32 v[150:151], v[150:151], v[148:149]
	v_cvt_pk_bf16_f32 v204, v150, v151
	global_store_dword v1, v204, s[20:21]
	v_pk_fma_f32 v[146:147], v[10:11], v[126:127], v[46:47]
	v_pk_fma_f32 v[148:149], v[28:29], v[128:129], v[48:49]
	v_pk_fma_f32 v[146:147], v[12:13], v[54:55], v[146:147]
	v_pk_fma_f32 v[148:149], v[30:31], v[56:57], v[148:149]
	v_pk_fma_f32 v[146:147], v[14:15], v[78:79], v[146:147]
	v_pk_fma_f32 v[148:149], v[32:33], v[80:81], v[148:149]
	v_pk_fma_f32 v[146:147], v[16:17], v[130:131], v[146:147]
	v_pk_fma_f32 v[148:149], v[34:35], v[132:133], v[148:149]
	v_pk_fma_f32 v[146:147], v[18:19], v[58:59], v[146:147]
	v_pk_fma_f32 v[148:149], v[36:37], v[60:61], v[148:149]
	v_pk_fma_f32 v[146:147], v[20:21], v[82:83], v[146:147]
	v_pk_fma_f32 v[148:149], v[38:39], v[84:85], v[148:149]
	v_pk_fma_f32 v[146:147], v[22:23], v[134:135], v[146:147]
	v_pk_fma_f32 v[148:149], v[40:41], v[136:137], v[148:149]
	v_pk_fma_f32 v[146:147], v[24:25], v[62:63], v[146:147]
	v_pk_fma_f32 v[148:149], v[42:43], v[64:65], v[148:149]
	v_pk_fma_f32 v[146:147], v[26:27], v[86:87], v[146:147]
	v_pk_fma_f32 v[148:149], v[44:45], v[88:89], v[148:149]
	v_pk_mul_f32 v[150:151], v[146:147], v[4:5]
	v_exp_f32_e32 v150, v150
	v_exp_f32_e32 v151, v151
	s_nop 0
	v_pk_add_f32 v[150:151], v[150:151], v[6:7]
	v_rcp_f32_e32 v150, v150
	v_rcp_f32_e32 v151, v151
	s_nop 0
	v_pk_mul_f32 v[150:151], v[150:151], v[146:147]
	v_pk_mul_f32 v[150:151], v[150:151], v[148:149]
	v_cvt_pk_bf16_f32 v205, v150, v151
	global_store_dword v1, v205, s[22:23]
	v_pk_fma_f32 v[146:147], v[10:11], v[130:131], v[46:47]
	v_pk_fma_f32 v[148:149], v[28:29], v[132:133], v[48:49]
	v_pk_fma_f32 v[146:147], v[12:13], v[58:59], v[146:147]
	v_pk_fma_f32 v[148:149], v[30:31], v[60:61], v[148:149]
	v_pk_fma_f32 v[146:147], v[14:15], v[82:83], v[146:147]
	v_pk_fma_f32 v[148:149], v[32:33], v[84:85], v[148:149]
	v_pk_fma_f32 v[146:147], v[16:17], v[134:135], v[146:147]
	v_pk_fma_f32 v[148:149], v[34:35], v[136:137], v[148:149]
	v_pk_fma_f32 v[146:147], v[18:19], v[62:63], v[146:147]
	v_pk_fma_f32 v[148:149], v[36:37], v[64:65], v[148:149]
	v_pk_fma_f32 v[146:147], v[20:21], v[86:87], v[146:147]
	v_pk_fma_f32 v[148:149], v[38:39], v[88:89], v[148:149]
	v_pk_fma_f32 v[146:147], v[22:23], v[138:139], v[146:147]
	v_pk_fma_f32 v[148:149], v[40:41], v[140:141], v[148:149]
	v_pk_fma_f32 v[146:147], v[24:25], v[66:67], v[146:147]
	v_pk_fma_f32 v[148:149], v[42:43], v[68:69], v[148:149]
	v_pk_fma_f32 v[146:147], v[26:27], v[90:91], v[146:147]
	v_pk_fma_f32 v[148:149], v[44:45], v[92:93], v[148:149]
	v_pk_mul_f32 v[150:151], v[146:147], v[4:5]
	v_exp_f32_e32 v150, v150
	v_exp_f32_e32 v151, v151
	s_nop 0
	v_pk_add_f32 v[150:151], v[150:151], v[6:7]
	v_rcp_f32_e32 v150, v150
	v_rcp_f32_e32 v151, v151
	s_nop 0
	v_pk_mul_f32 v[150:151], v[150:151], v[146:147]
	v_pk_mul_f32 v[150:151], v[150:151], v[148:149]
	v_cvt_pk_bf16_f32 v206, v150, v151
	global_store_dword v1, v206, s[24:25]
	v_pk_fma_f32 v[146:147], v[10:11], v[134:135], v[46:47]
	v_pk_fma_f32 v[148:149], v[28:29], v[136:137], v[48:49]
	v_pk_fma_f32 v[146:147], v[12:13], v[62:63], v[146:147]
	v_pk_fma_f32 v[148:149], v[30:31], v[64:65], v[148:149]
	v_pk_fma_f32 v[146:147], v[14:15], v[86:87], v[146:147]
	v_pk_fma_f32 v[148:149], v[32:33], v[88:89], v[148:149]
	v_pk_fma_f32 v[146:147], v[16:17], v[138:139], v[146:147]
	v_pk_fma_f32 v[148:149], v[34:35], v[140:141], v[148:149]
	v_pk_fma_f32 v[146:147], v[18:19], v[66:67], v[146:147]
	v_pk_fma_f32 v[148:149], v[36:37], v[68:69], v[148:149]
	v_pk_fma_f32 v[146:147], v[20:21], v[90:91], v[146:147]
	v_pk_fma_f32 v[148:149], v[38:39], v[92:93], v[148:149]
	v_pk_fma_f32 v[146:147], v[22:23], v[142:143], v[146:147]
	v_pk_fma_f32 v[148:149], v[40:41], v[144:145], v[148:149]
	v_pk_fma_f32 v[146:147], v[24:25], v[70:71], v[146:147]
	v_pk_fma_f32 v[148:149], v[42:43], v[72:73], v[148:149]
	v_pk_fma_f32 v[146:147], v[26:27], v[94:95], v[146:147]
	v_pk_fma_f32 v[148:149], v[44:45], v[96:97], v[148:149]
	v_pk_mul_f32 v[150:151], v[146:147], v[4:5]
	v_exp_f32_e32 v150, v150
	v_exp_f32_e32 v151, v151
	s_nop 0
	v_pk_add_f32 v[150:151], v[150:151], v[6:7]
	v_rcp_f32_e32 v150, v150
	v_rcp_f32_e32 v151, v151
	s_nop 0
	v_pk_mul_f32 v[150:151], v[150:151], v[146:147]
	v_pk_mul_f32 v[150:151], v[150:151], v[148:149]
	v_cvt_pk_bf16_f32 v207, v150, v151
	global_store_dword v1, v207, s[26:27]
	s_add_u32 s20, s20, 0x2c00
	s_addc_u32 s21, s21, 0
	s_add_u32 s22, s22, 0x2c00
	s_addc_u32 s23, s23, 0
	s_add_u32 s24, s24, 0x2c00
	s_addc_u32 s25, s25, 0
	s_add_u32 s26, s26, 0x2c00
	s_addc_u32 s27, s27, 0
	s_add_u32 s32, s32, 1
	s_cmp_lt_u32 s32, 8
	s_cbranch_scc1 .Lffn_p9e_loop_lat1
	s_waitcnt vmcnt(0)
	s_branch .LBB0_1180

.Lffn_p9_item:
	s_cmp_ge_u32 s6, 3200
	s_cbranch_scc1 .Lffn_p9_done
	s_mov_b64 s[44:45], exec
	s_mov_b64 exec, 1
	global_atomic_add v8, v9, v208, s[4:5] sc0
	s_mov_b64 exec, s[44:45]
	s_cmp_ge_u32 s6, 384
	s_cbranch_scc1 .Lffn_p9_ctx
	s_cmp_ge_u32 s6, 256
	s_cbranch_scc1 .Lffn_p9_late
	s_add_u32 s35, s6, 1024
	s_mul_i32 s33, s35, 52429
	s_lshr_b32 s33, s33, 21
	s_mul_i32 s34, s33, 40
	s_sub_u32 s43, s35, s34
	s_branch .Lffn_p9_dolat
.Lffn_p9_late:
	s_sub_u32 s35, s6, 256
	s_lshr_b32 s33, s35, 2
	s_and_b32 s43, s35, 3
	s_add_u32 s43, s43, 40
.Lffn_p9_dolat:
	s_and_b32 s34, s33, 1
	s_bfe_u32 s35, s33, 0x20001
	s_lshr_b32 s36, s33, 3
	s_cmp_lg_u32 s35, 0
	s_cselect_b32 s28, -1, 0
	s_cmp_lg_u32 s35, 3
	s_cselect_b32 s29, -1, 0
	s_cmp_lg_u32 s34, 0
	s_cselect_b32 s30, -1, 0
	s_cselect_b32 s31, 0, -1
	s_lshl_b32 s36, s36, 10
	s_lshl_b32 s35, s35, 8
	s_lshl_b32 s34, s34, 5
	s_add_u32 s36, s36, s35
	s_add_u32 s36, s36, s34
	s_add_u32 s36, s36, 4096
	v_and_b32_e32 v1, 63, v154
	v_lshlrev_b32_e32 v1, 2, v1
	s_lshl_b32 s33, s43, 8
	v_add_u32_e32 v1, s33, v1
	v_add_u32_e32 v2, 0x2c00, v1
	v_lshlrev_b32_e32 v3, 1, v1
	s_add_i32 s33, s36, 0
	s_mul_i32 s33, s33, 0x2c00
	s_add_u32 s20, s40, s33
	s_addc_u32 s21, s41, 0
	s_add_i32 s33, s36, 64
	s_mul_i32 s33, s33, 0x2c00
	s_add_u32 s22, s40, s33
	s_addc_u32 s23, s41, 0
	s_add_i32 s33, s36, 128
	s_mul_i32 s33, s33, 0x2c00
	s_add_u32 s24, s40, s33
	s_addc_u32 s25, s41, 0
	s_add_i32 s33, s36, 192
	s_mul_i32 s33, s33, 0x2c00
	s_add_u32 s26, s40, s33
	s_addc_u32 s27, s41, 0
	s_add_i32 s33, s36, -65
	s_mul_i32 s33, s33, 0x5800
	s_ashr_i32 s34, s33, 31
	s_add_u32 s8, s38, s33
	s_addc_u32 s9, s39, s34
	s_add_i32 s33, s36, -1
	s_mul_i32 s33, s33, 0x5800
	s_ashr_i32 s34, s33, 31
	s_add_u32 s10, s38, s33
	s_addc_u32 s11, s39, s34
	s_add_i32 s33, s36, 63
	s_mul_i32 s33, s33, 0x5800
	s_ashr_i32 s34, s33, 31
	s_add_u32 s12, s38, s33
	s_addc_u32 s13, s39, s34
	s_add_i32 s33, s36, 127
	s_mul_i32 s33, s33, 0x5800
	s_ashr_i32 s34, s33, 31
	s_add_u32 s14, s38, s33
	s_addc_u32 s15, s39, s34
	s_add_i32 s33, s36, 191
	s_mul_i32 s33, s33, 0x5800
	s_ashr_i32 s34, s33, 31
	s_add_u32 s16, s38, s33
	s_addc_u32 s17, s39, s34
	s_add_i32 s33, s36, 255
	s_mul_i32 s33, s33, 0x5800
	s_ashr_i32 s34, s33, 31
	s_add_u32 s18, s38, s33
	s_addc_u32 s19, s39, s34
	s_add_u32 s33, s0, 0x0
	s_addc_u32 s34, s1, 0
	s_mov_b32 s36, s33
	s_mov_b32 s37, s34
	global_load_dwordx2 v[10:11], v3, s[36:37]
	s_add_u32 s36, s36, 0x5800
	s_addc_u32 s37, s37, 0
	global_load_dwordx2 v[28:29], v3, s[36:37]
	s_add_u32 s33, s0, 0xb000
	s_addc_u32 s34, s1, 0
	s_mov_b32 s36, s33
	s_mov_b32 s37, s34
	global_load_dwordx2 v[12:13], v3, s[36:37]
	s_add_u32 s36, s36, 0x5800
	s_addc_u32 s37, s37, 0
	global_load_dwordx2 v[30:31], v3, s[36:37]
	s_add_u32 s33, s0, 0x16000
	s_addc_u32 s34, s1, 0
	s_mov_b32 s36, s33
	s_mov_b32 s37, s34
	global_load_dwordx2 v[14:15], v3, s[36:37]
	s_add_u32 s36, s36, 0x5800
	s_addc_u32 s37, s37, 0
	global_load_dwordx2 v[32:33], v3, s[36:37]
	s_add_u32 s33, s0, 0x21000
	s_addc_u32 s34, s1, 0
	s_mov_b32 s36, s33
	s_mov_b32 s37, s34
	global_load_dwordx2 v[16:17], v3, s[36:37]
	s_add_u32 s36, s36, 0x5800
	s_addc_u32 s37, s37, 0
	global_load_dwordx2 v[34:35], v3, s[36:37]
	s_add_u32 s33, s0, 0x2c000
	s_addc_u32 s34, s1, 0
	s_mov_b32 s36, s33
	s_mov_b32 s37, s34
	global_load_dwordx2 v[18:19], v3, s[36:37]
	s_add_u32 s36, s36, 0x5800
	s_addc_u32 s37, s37, 0
	global_load_dwordx2 v[36:37], v3, s[36:37]
	s_add_u32 s33, s0, 0x37000
	s_addc_u32 s34, s1, 0
	s_mov_b32 s36, s33
	s_mov_b32 s37, s34
	global_load_dwordx2 v[20:21], v3, s[36:37]
	s_add_u32 s36, s36, 0x5800
	s_addc_u32 s37, s37, 0
	global_load_dwordx2 v[38:39], v3, s[36:37]
	s_add_u32 s33, s0, 0x42000
	s_addc_u32 s34, s1, 0
	s_mov_b32 s36, s33
	s_mov_b32 s37, s34
	global_load_dwordx2 v[22:23], v3, s[36:37]
	s_add_u32 s36, s36, 0x5800
	s_addc_u32 s37, s37, 0
	global_load_dwordx2 v[40:41], v3, s[36:37]
	s_add_u32 s33, s0, 0x4d000
	s_addc_u32 s34, s1, 0
	s_mov_b32 s36, s33
	s_mov_b32 s37, s34
	global_load_dwordx2 v[24:25], v3, s[36:37]
	s_add_u32 s36, s36, 0x5800
	s_addc_u32 s37, s37, 0
	global_load_dwordx2 v[42:43], v3, s[36:37]
	s_add_u32 s33, s0, 0x58000
	s_addc_u32 s34, s1, 0
	s_mov_b32 s36, s33
	s_mov_b32 s37, s34
	global_load_dwordx2 v[26:27], v3, s[36:37]
	s_add_u32 s36, s36, 0x5800
	s_addc_u32 s37, s37, 0
	global_load_dwordx2 v[44:45], v3, s[36:37]
	global_load_dwordx2 v[46:47], v3, s[2:3]
	s_add_u32 s36, s2, 0x5800
	s_addc_u32 s37, s3, 0
	global_load_dwordx2 v[48:49], v3, s[36:37]
	global_load_dword v180, v1, s[8:9]
	global_load_dword v181, v2, s[8:9]
	global_load_dword v182, v1, s[10:11]
	global_load_dword v183, v2, s[10:11]
	global_load_dword v184, v1, s[12:13]
	global_load_dword v185, v2, s[12:13]
	global_load_dword v186, v1, s[14:15]
	global_load_dword v187, v2, s[14:15]
	global_load_dword v188, v1, s[16:17]
	global_load_dword v189, v2, s[16:17]
	global_load_dword v190, v1, s[18:19]
	global_load_dword v191, v2, s[18:19]
	s_add_u32 s8, s8, 0x5800
	s_addc_u32 s9, s9, 0
	s_add_u32 s10, s10, 0x5800
	s_addc_u32 s11, s11, 0
	s_add_u32 s12, s12, 0x5800
	s_addc_u32 s13, s13, 0
	s_add_u32 s14, s14, 0x5800
	s_addc_u32 s15, s15, 0
	s_add_u32 s16, s16, 0x5800
	s_addc_u32 s17, s17, 0
	s_add_u32 s18, s18, 0x5800
	s_addc_u32 s19, s19, 0
	global_load_dword v192, v1, s[8:9]
	global_load_dword v193, v2, s[8:9]
	global_load_dword v194, v1, s[10:11]
	global_load_dword v195, v2, s[10:11]
	global_load_dword v196, v1, s[12:13]
	global_load_dword v197, v2, s[12:13]
	global_load_dword v198, v1, s[14:15]
	global_load_dword v199, v2, s[14:15]
	global_load_dword v200, v1, s[16:17]
	global_load_dword v201, v2, s[16:17]
	global_load_dword v202, v1, s[18:19]
	global_load_dword v203, v2, s[18:19]
	s_add_u32 s8, s8, 0x5800
	s_addc_u32 s9, s9, 0
	s_add_u32 s10, s10, 0x5800
	s_addc_u32 s11, s11, 0
	s_add_u32 s12, s12, 0x5800
	s_addc_u32 s13, s13, 0
	s_add_u32 s14, s14, 0x5800
	s_addc_u32 s15, s15, 0
	s_add_u32 s16, s16, 0x5800
	s_addc_u32 s17, s17, 0
	s_add_u32 s18, s18, 0x5800
	s_addc_u32 s19, s19, 0
	global_load_dword v156, v1, s[8:9]
	global_load_dword v157, v2, s[8:9]
	global_load_dword v158, v1, s[10:11]
	global_load_dword v159, v2, s[10:11]
	global_load_dword v160, v1, s[12:13]
	global_load_dword v161, v2, s[12:13]
	global_load_dword v162, v1, s[14:15]
	global_load_dword v163, v2, s[14:15]
	global_load_dword v164, v1, s[16:17]
	global_load_dword v165, v2, s[16:17]
	global_load_dword v166, v1, s[18:19]
	global_load_dword v167, v2, s[18:19]
	s_add_u32 s8, s8, 0x5800
	s_addc_u32 s9, s9, 0
	s_add_u32 s10, s10, 0x5800
	s_addc_u32 s11, s11, 0
	s_add_u32 s12, s12, 0x5800
	s_addc_u32 s13, s13, 0
	s_add_u32 s14, s14, 0x5800
	s_addc_u32 s15, s15, 0
	s_add_u32 s16, s16, 0x5800
	s_addc_u32 s17, s17, 0
	s_add_u32 s18, s18, 0x5800
	s_addc_u32 s19, s19, 0
	global_load_dword v168, v1, s[8:9]
	global_load_dword v169, v2, s[8:9]
	global_load_dword v170, v1, s[10:11]
	global_load_dword v171, v2, s[10:11]
	global_load_dword v172, v1, s[12:13]
	global_load_dword v173, v2, s[12:13]
	global_load_dword v174, v1, s[14:15]
	global_load_dword v175, v2, s[14:15]
	global_load_dword v176, v1, s[16:17]
	global_load_dword v177, v2, s[16:17]
	global_load_dword v178, v1, s[18:19]
	global_load_dword v179, v2, s[18:19]
	s_add_u32 s8, s8, 0x5800
	s_addc_u32 s9, s9, 0
	s_add_u32 s10, s10, 0x5800
	s_addc_u32 s11, s11, 0
	s_add_u32 s12, s12, 0x5800
	s_addc_u32 s13, s13, 0
	s_add_u32 s14, s14, 0x5800
	s_addc_u32 s15, s15, 0
	s_add_u32 s16, s16, 0x5800
	s_addc_u32 s17, s17, 0
	s_add_u32 s18, s18, 0x5800
	s_addc_u32 s19, s19, 0
	s_waitcnt vmcnt(24)
	v_and_b32_e32 v180, s30, v180
	v_and_b32_e32 v181, s30, v181
	v_and_b32_e32 v180, s28, v180
	v_and_b32_e32 v181, s28, v181
	v_lshlrev_b32_e32 v50, 16, v180
	v_and_b32_e32 v51, 0xffff0000, v180
	v_lshlrev_b32_e32 v52, 16, v181
	v_and_b32_e32 v53, 0xffff0000, v181
	v_and_b32_e32 v182, s30, v182
	v_and_b32_e32 v183, s30, v183
	v_lshlrev_b32_e32 v54, 16, v182
	v_and_b32_e32 v55, 0xffff0000, v182
	v_lshlrev_b32_e32 v56, 16, v183
	v_and_b32_e32 v57, 0xffff0000, v183
	v_and_b32_e32 v184, s30, v184
	v_and_b32_e32 v185, s30, v185
	v_lshlrev_b32_e32 v58, 16, v184
	v_and_b32_e32 v59, 0xffff0000, v184
	v_lshlrev_b32_e32 v60, 16, v185
	v_and_b32_e32 v61, 0xffff0000, v185
	v_and_b32_e32 v186, s30, v186
	v_and_b32_e32 v187, s30, v187
	v_lshlrev_b32_e32 v62, 16, v186
	v_and_b32_e32 v63, 0xffff0000, v186
	v_lshlrev_b32_e32 v64, 16, v187
	v_and_b32_e32 v65, 0xffff0000, v187
	v_and_b32_e32 v188, s30, v188
	v_and_b32_e32 v189, s30, v189
	v_lshlrev_b32_e32 v66, 16, v188
	v_and_b32_e32 v67, 0xffff0000, v188
	v_lshlrev_b32_e32 v68, 16, v189
	v_and_b32_e32 v69, 0xffff0000, v189
	v_and_b32_e32 v190, s30, v190
	v_and_b32_e32 v191, s30, v191
	v_and_b32_e32 v190, s29, v190
	v_and_b32_e32 v191, s29, v191
	v_lshlrev_b32_e32 v70, 16, v190
	v_and_b32_e32 v71, 0xffff0000, v190
	v_lshlrev_b32_e32 v72, 16, v191
	v_and_b32_e32 v73, 0xffff0000, v191
	v_and_b32_e32 v192, s28, v192
	v_and_b32_e32 v193, s28, v193
	v_lshlrev_b32_e32 v74, 16, v192
	v_and_b32_e32 v75, 0xffff0000, v192
	v_lshlrev_b32_e32 v76, 16, v193
	v_and_b32_e32 v77, 0xffff0000, v193
	v_lshlrev_b32_e32 v78, 16, v194
	v_and_b32_e32 v79, 0xffff0000, v194
	v_lshlrev_b32_e32 v80, 16, v195
	v_and_b32_e32 v81, 0xffff0000, v195
	v_lshlrev_b32_e32 v82, 16, v196
	v_and_b32_e32 v83, 0xffff0000, v196
	v_lshlrev_b32_e32 v84, 16, v197
	v_and_b32_e32 v85, 0xffff0000, v197
	v_lshlrev_b32_e32 v86, 16, v198
	v_and_b32_e32 v87, 0xffff0000, v198
	v_lshlrev_b32_e32 v88, 16, v199
	v_and_b32_e32 v89, 0xffff0000, v199
	v_lshlrev_b32_e32 v90, 16, v200
	v_and_b32_e32 v91, 0xffff0000, v200
	v_lshlrev_b32_e32 v92, 16, v201
	v_and_b32_e32 v93, 0xffff0000, v201
	v_and_b32_e32 v202, s29, v202
	v_and_b32_e32 v203, s29, v203
	v_lshlrev_b32_e32 v94, 16, v202
	v_and_b32_e32 v95, 0xffff0000, v202
	v_lshlrev_b32_e32 v96, 16, v203
	v_and_b32_e32 v97, 0xffff0000, v203
	global_load_dword v180, v1, s[8:9]
	global_load_dword v181, v2, s[8:9]
	global_load_dword v182, v1, s[10:11]
	global_load_dword v183, v2, s[10:11]
	global_load_dword v184, v1, s[12:13]
	global_load_dword v185, v2, s[12:13]
	global_load_dword v186, v1, s[14:15]
	global_load_dword v187, v2, s[14:15]
	global_load_dword v188, v1, s[16:17]
	global_load_dword v189, v2, s[16:17]
	global_load_dword v190, v1, s[18:19]
	global_load_dword v191, v2, s[18:19]
	s_add_u32 s8, s8, 0x5800
	s_addc_u32 s9, s9, 0
	s_add_u32 s10, s10, 0x5800
	s_addc_u32 s11, s11, 0
	s_add_u32 s12, s12, 0x5800
	s_addc_u32 s13, s13, 0
	s_add_u32 s14, s14, 0x5800
	s_addc_u32 s15, s15, 0
	s_add_u32 s16, s16, 0x5800
	s_addc_u32 s17, s17, 0
	s_add_u32 s18, s18, 0x5800
	s_addc_u32 s19, s19, 0
	global_load_dword v192, v1, s[8:9]
	global_load_dword v193, v2, s[8:9]
	global_load_dword v194, v1, s[10:11]
	global_load_dword v195, v2, s[10:11]
	global_load_dword v196, v1, s[12:13]
	global_load_dword v197, v2, s[12:13]
	global_load_dword v198, v1, s[14:15]
	global_load_dword v199, v2, s[14:15]
	global_load_dword v200, v1, s[16:17]
	global_load_dword v201, v2, s[16:17]
	global_load_dword v202, v1, s[18:19]
	global_load_dword v203, v2, s[18:19]
	s_add_u32 s8, s8, 0x5800
	s_addc_u32 s9, s9, 0
	s_add_u32 s10, s10, 0x5800
	s_addc_u32 s11, s11, 0
	s_add_u32 s12, s12, 0x5800
	s_addc_u32 s13, s13, 0
	s_add_u32 s14, s14, 0x5800
	s_addc_u32 s15, s15, 0
	s_add_u32 s16, s16, 0x5800
	s_addc_u32 s17, s17, 0
	s_add_u32 s18, s18, 0x5800
	s_addc_u32 s19, s19, 0
	s_mov_b32 s32, 0

.Lffn_p9_ctx:
	s_sub_u32 s35, s6, 384
	s_mul_i32 s33, s35, 47663
	s_lshr_b32 s33, s33, 21
	s_mul_i32 s34, s33, 44
	s_sub_u32 s43, s35, s34
	s_and_b32 s34, s33, 3
	s_lshr_b32 s36, s33, 2
	s_mov_b32 s28, -1
	s_mov_b32 s29, -1
	s_cmp_lg_u32 s34, 0
	s_cselect_b32 s30, -1, 0
	s_cmp_lg_u32 s34, 3
	s_cselect_b32 s31, -1, 0
	s_lshl_b32 s36, s36, 8
	s_lshl_b32 s34, s34, 6
	s_add_u32 s36, s36, s34
	v_and_b32_e32 v1, 63, v154
	v_lshlrev_b32_e32 v1, 2, v1
	s_lshl_b32 s33, s43, 8
	v_add_u32_e32 v1, s33, v1
	v_add_u32_e32 v2, 0x2c00, v1
	v_lshlrev_b32_e32 v3, 1, v1
	s_add_i32 s33, s36, 0
	s_mul_i32 s33, s33, 0x2c00
	s_add_u32 s20, s40, s33
	s_addc_u32 s21, s41, 0
	s_add_i32 s33, s36, -1
	s_mul_i32 s33, s33, 0x5800
	s_ashr_i32 s34, s33, 31
	s_add_u32 s8, s38, s33
	s_addc_u32 s9, s39, s34
	s_add_u32 s33, s0, 0x0
	s_addc_u32 s34, s1, 0
	s_mov_b32 s36, s33
	s_mov_b32 s37, s34
	global_load_dwordx2 v[10:11], v3, s[36:37]
	s_add_u32 s36, s36, 0x5800
	s_addc_u32 s37, s37, 0
	global_load_dwordx2 v[28:29], v3, s[36:37]
	s_add_u32 s33, s0, 0xb000
	s_addc_u32 s34, s1, 0
	s_mov_b32 s36, s33
	s_mov_b32 s37, s34
	global_load_dwordx2 v[12:13], v3, s[36:37]
	s_add_u32 s36, s36, 0x5800
	s_addc_u32 s37, s37, 0
	global_load_dwordx2 v[30:31], v3, s[36:37]
	s_add_u32 s33, s0, 0x16000
	s_addc_u32 s34, s1, 0
	s_mov_b32 s36, s33
	s_mov_b32 s37, s34
	global_load_dwordx2 v[14:15], v3, s[36:37]
	s_add_u32 s36, s36, 0x5800
	s_addc_u32 s37, s37, 0
	global_load_dwordx2 v[32:33], v3, s[36:37]
	s_add_u32 s33, s0, 0x21000
	s_addc_u32 s34, s1, 0
	s_mov_b32 s36, s33
	s_mov_b32 s37, s34
	global_load_dwordx2 v[16:17], v3, s[36:37]
	s_add_u32 s36, s36, 0x5800
	s_addc_u32 s37, s37, 0
	global_load_dwordx2 v[34:35], v3, s[36:37]
	s_add_u32 s33, s0, 0x2c000
	s_addc_u32 s34, s1, 0
	s_mov_b32 s36, s33
	s_mov_b32 s37, s34
	global_load_dwordx2 v[18:19], v3, s[36:37]
	s_add_u32 s36, s36, 0x5800
	s_addc_u32 s37, s37, 0
	global_load_dwordx2 v[36:37], v3, s[36:37]
	s_add_u32 s33, s0, 0x37000
	s_addc_u32 s34, s1, 0
	s_mov_b32 s36, s33
	s_mov_b32 s37, s34
	global_load_dwordx2 v[20:21], v3, s[36:37]
	s_add_u32 s36, s36, 0x5800
	s_addc_u32 s37, s37, 0
	global_load_dwordx2 v[38:39], v3, s[36:37]
	s_add_u32 s33, s0, 0x42000
	s_addc_u32 s34, s1, 0
	s_mov_b32 s36, s33
	s_mov_b32 s37, s34
	global_load_dwordx2 v[22:23], v3, s[36:37]
	s_add_u32 s36, s36, 0x5800
	s_addc_u32 s37, s37, 0
	global_load_dwordx2 v[40:41], v3, s[36:37]
	s_add_u32 s33, s0, 0x4d000
	s_addc_u32 s34, s1, 0
	s_mov_b32 s36, s33
	s_mov_b32 s37, s34
	global_load_dwordx2 v[24:25], v3, s[36:37]
	s_add_u32 s36, s36, 0x5800
	s_addc_u32 s37, s37, 0
	global_load_dwordx2 v[42:43], v3, s[36:37]
	s_add_u32 s33, s0, 0x58000
	s_addc_u32 s34, s1, 0
	s_mov_b32 s36, s33
	s_mov_b32 s37, s34
	global_load_dwordx2 v[26:27], v3, s[36:37]
	s_add_u32 s36, s36, 0x5800
	s_addc_u32 s37, s37, 0
	global_load_dwordx2 v[44:45], v3, s[36:37]
	global_load_dwordx2 v[46:47], v3, s[2:3]
	s_add_u32 s36, s2, 0x5800
	s_addc_u32 s37, s3, 0
	global_load_dwordx2 v[48:49], v3, s[36:37]
	global_load_dword v172, v1, s[8:9]
	global_load_dword v173, v2, s[8:9]
	s_add_u32 s8, s8, 0x5800
	s_addc_u32 s9, s9, 0
	global_load_dword v174, v1, s[8:9]
	global_load_dword v175, v2, s[8:9]
	s_add_u32 s8, s8, 0x5800
	s_addc_u32 s9, s9, 0
	global_load_dword v156, v1, s[8:9]
	global_load_dword v157, v2, s[8:9]
	s_add_u32 s8, s8, 0x5800
	s_addc_u32 s9, s9, 0
	global_load_dword v158, v1, s[8:9]
	global_load_dword v159, v2, s[8:9]
	s_add_u32 s8, s8, 0x5800
	s_addc_u32 s9, s9, 0
	global_load_dword v160, v1, s[8:9]
	global_load_dword v161, v2, s[8:9]
	s_add_u32 s8, s8, 0x5800
	s_addc_u32 s9, s9, 0
	global_load_dword v162, v1, s[8:9]
	global_load_dword v163, v2, s[8:9]
	s_add_u32 s8, s8, 0x5800
	s_addc_u32 s9, s9, 0
	global_load_dword v164, v1, s[8:9]
	global_load_dword v165, v2, s[8:9]
	s_add_u32 s8, s8, 0x5800
	s_addc_u32 s9, s9, 0
	global_load_dword v166, v1, s[8:9]
	global_load_dword v167, v2, s[8:9]
	s_add_u32 s8, s8, 0x5800
	s_addc_u32 s9, s9, 0
	global_load_dword v168, v1, s[8:9]
	global_load_dword v169, v2, s[8:9]
	s_add_u32 s8, s8, 0x5800
	s_addc_u32 s9, s9, 0
	global_load_dword v170, v1, s[8:9]
	global_load_dword v171, v2, s[8:9]
	s_add_u32 s8, s8, 0x5800
	s_addc_u32 s9, s9, 0
	s_waitcnt vmcnt(16)
	v_and_b32_e32 v172, s30, v172
	v_and_b32_e32 v173, s30, v173
	v_lshlrev_b32_e32 v82, 16, v172
	v_and_b32_e32 v83, 0xffff0000, v172
	v_lshlrev_b32_e32 v84, 16, v173
	v_and_b32_e32 v85, 0xffff0000, v173
	v_lshlrev_b32_e32 v86, 16, v174
	v_and_b32_e32 v87, 0xffff0000, v174
	v_lshlrev_b32_e32 v88, 16, v175
	v_and_b32_e32 v89, 0xffff0000, v175
	global_load_dword v172, v1, s[8:9]
	global_load_dword v173, v2, s[8:9]
	s_add_u32 s8, s8, 0x5800
	s_addc_u32 s9, s9, 0
	global_load_dword v174, v1, s[8:9]
	global_load_dword v175, v2, s[8:9]
	s_add_u32 s8, s8, 0x5800
	s_addc_u32 s9, s9, 0
	global_load_dword v176, v1, s[8:9]
	global_load_dword v177, v2, s[8:9]
	s_add_u32 s8, s8, 0x5800
	s_addc_u32 s9, s9, 0
	global_load_dword v178, v1, s[8:9]
	global_load_dword v179, v2, s[8:9]
	s_add_u32 s8, s8, 0x5800
	s_addc_u32 s9, s9, 0
	global_load_dword v180, v1, s[8:9]
	global_load_dword v181, v2, s[8:9]
	s_add_u32 s8, s8, 0x5800
	s_addc_u32 s9, s9, 0
	global_load_dword v182, v1, s[8:9]
	global_load_dword v183, v2, s[8:9]
	s_add_u32 s8, s8, 0x5800
	s_addc_u32 s9, s9, 0
	global_load_dword v184, v1, s[8:9]
	global_load_dword v185, v2, s[8:9]
	s_add_u32 s8, s8, 0x5800
	s_addc_u32 s9, s9, 0
	global_load_dword v186, v1, s[8:9]
	global_load_dword v187, v2, s[8:9]
	s_add_u32 s8, s8, 0x5800
	s_addc_u32 s9, s9, 0
	s_mov_b32 s32, 0
